# v26 plus 64-byte alignment of the hot GEMM and attention loop heads
# baseline (speedup 1.0000x reference)
.Lgqa_stag_in:
	.p2alignl 6, 3212836864

.LBB0_138:
	v_add_f32_e32 v2, v128, v207
	v_add_f32_e32 v2, 0, v2
	v_add_f32_e32 v3, v129, v208
	v_add_f32_e32 v2, v3, v2
	v_add_f32_e32 v3, v130, v209
	v_add_f32_e32 v2, v3, v2
	v_add_f32_e32 v3, v131, v220
	v_add_f32_e32 v2, v3, v2
	v_add_f32_e32 v3, v132, v116
	v_add_f32_e32 v2, v3, v2
	v_add_f32_e32 v3, v133, v117
	v_add_f32_e32 v2, v3, v2
	v_add_f32_e32 v3, v134, v118
	v_add_f32_e32 v2, v3, v2
	v_add_f32_e32 v3, v135, v119
	v_add_f32_e32 v2, v3, v2
	v_add_f32_e32 v3, v136, v120
	v_add_f32_e32 v2, v3, v2
	v_add_f32_e32 v3, v137, v121
	v_add_f32_e32 v2, v3, v2
	v_add_f32_e32 v3, v138, v122
	v_add_f32_e32 v2, v3, v2
	v_add_f32_e32 v3, v139, v123
	v_add_f32_e32 v2, v3, v2
	v_add_f32_e32 v3, v140, v124
	v_add_f32_e32 v2, v3, v2
	v_add_f32_e32 v3, v141, v125
	v_add_f32_e32 v2, v3, v2
	v_add_f32_e32 v3, v142, v126
	v_add_f32_e32 v2, v3, v2
	v_add_f32_e32 v3, v143, v127
	v_add_f32_e32 v2, v3, v2
	v_fmac_f32_e32 v2, v205, v0
	v_add_f32_e32 v0, v96, v80
	v_add_f32_e32 v0, 0, v0
	v_add_f32_e32 v3, v97, v81
	v_add_f32_e32 v0, v3, v0
	v_add_f32_e32 v3, v98, v82
	v_add_f32_e32 v0, v3, v0
	v_add_f32_e32 v3, v99, v83
	v_add_f32_e32 v0, v3, v0
	v_add_f32_e32 v3, v100, v84
	v_add_f32_e32 v0, v3, v0
	v_add_f32_e32 v3, v101, v85
	v_add_f32_e32 v0, v3, v0
	v_add_f32_e32 v3, v102, v86
	v_add_f32_e32 v0, v3, v0
	v_add_f32_e32 v3, v103, v87
	v_add_f32_e32 v0, v3, v0
	v_add_f32_e32 v3, v104, v88
	v_add_f32_e32 v0, v3, v0
	v_add_f32_e32 v3, v105, v89
	v_add_f32_e32 v0, v3, v0
	v_add_f32_e32 v3, v106, v90
	v_add_f32_e32 v0, v3, v0
	v_add_f32_e32 v3, v107, v91
	v_add_f32_e32 v0, v3, v0
	v_add_f32_e32 v3, v108, v92
	v_add_f32_e32 v0, v3, v0
	v_add_f32_e32 v3, v109, v93
	v_add_f32_e32 v0, v3, v0
	v_add_f32_e32 v3, v110, v94
	v_add_f32_e32 v0, v3, v0
	v_add_f32_e32 v3, v111, v95
	v_add_f32_e32 v205, v3, v0
	s_add_i32 s37, s37, 1
	v_fmac_f32_e32 v205, v2, v14
	v_lshl_add_u64 v[192:193], v[192:193], 0, s[70:71]
	s_cmp_lg_u32 s37, 36
	v_lshl_add_u64 v[194:195], v[194:195], 0, s[88:89]
	s_waitcnt lgkmcnt(0)
	s_barrier
	s_cbranch_scc0 .LBB0_147
	.p2alignl 6, 3212836864

.LBB0_148:
	v_add_f32_e32 v98, v207, v208
	v_add_f32_e32 v98, 0, v98
	v_add_f32_e32 v99, v115, v209
	v_add_f32_e32 v66, v82, v66
	v_add_f32_e32 v98, v99, v98
	v_add_f32_e32 v99, v116, v220
	v_add_f32_e32 v66, 0, v66
	v_add_f32_e32 v67, v83, v67
	v_add_f32_e32 v98, v99, v98
	v_add_f32_e32 v99, v117, v221
	v_add_f32_e32 v66, v67, v66
	v_add_f32_e32 v67, v84, v68
	v_add_f32_e32 v98, v99, v98
	v_add_f32_e32 v99, v118, v222
	v_add_f32_e32 v66, v67, v66
	v_add_f32_e32 v67, v85, v69
	v_add_f32_e32 v98, v99, v98
	v_add_f32_e32 v99, v119, v223
	v_add_f32_e32 v66, v67, v66
	v_add_f32_e32 v67, v86, v70
	v_add_f32_e32 v98, v99, v98
	v_add_f32_e32 v99, v120, v224
	v_add_f32_e32 v66, v67, v66
	v_add_f32_e32 v67, v87, v71
	v_add_f32_e32 v98, v99, v98
	v_add_f32_e32 v99, v121, v225
	v_add_f32_e32 v66, v67, v66
	v_add_f32_e32 v67, v88, v72
	v_add_f32_e32 v98, v99, v98
	v_add_f32_e32 v99, v122, v226
	v_add_f32_e32 v66, v67, v66
	v_add_f32_e32 v67, v89, v73
	v_add_f32_e32 v98, v99, v98
	v_add_f32_e32 v99, v123, v227
	v_add_f32_e32 v66, v67, v66
	v_add_f32_e32 v67, v90, v74
	v_add_f32_e32 v98, v99, v98
	v_add_f32_e32 v99, v124, v228
	v_add_f32_e32 v66, v67, v66
	v_add_f32_e32 v67, v91, v75
	v_add_f32_e32 v98, v99, v98
	v_add_f32_e32 v99, v125, v229
	v_add_f32_e32 v66, v67, v66
	v_add_f32_e32 v67, v92, v76
	v_add_f32_e32 v98, v99, v98
	v_add_f32_e32 v99, v126, v230
	v_add_f32_e32 v66, v67, v66
	v_add_f32_e32 v67, v93, v77
	v_add_f32_e32 v98, v99, v98
	v_add_f32_e32 v99, v127, v231
	v_add_f32_e32 v66, v67, v66
	v_add_f32_e32 v67, v94, v78
	v_add_f32_e32 v98, v99, v98
	v_add_f32_e32 v99, v128, v232
	v_add_f32_e32 v66, v67, v66
	v_add_f32_e32 v67, v95, v79
	v_add_f32_e32 v98, v99, v98
	v_add_f32_e32 v99, v129, v233
	v_add_f32_e32 v66, v67, v66
	v_add_f32_e32 v67, v96, v80
	v_add_f32_e32 v98, v99, v98
	v_add_f32_e32 v66, v67, v66
	v_add_f32_e32 v67, v97, v81
	v_fmac_f32_e32 v98, v204, v192
	v_add_f32_e32 v204, v67, v66
	s_add_i32 s3, s3, 1
	v_fmac_f32_e32 v204, v98, v114
	v_lshl_add_u64 v[188:189], v[188:189], 0, s[70:71]
	s_cmp_lg_u32 s3, 36
	v_lshl_add_u64 v[190:191], v[190:191], 0, s[88:89]
	s_waitcnt lgkmcnt(0)
	s_barrier
	s_cbranch_scc0 .LBB0_136
	.p2alignl 6, 3212836864

.LBB0_185:
	global_load_dwordx4 v[144:147], v[208:209], off
	.p2alignl 6, 3212836864

.LBB0_307:
	s_add_u32 vcc_lo, s82, 0x80
	s_addc_u32 vcc_hi, s83, 0
	s_add_u32 s82, s42, 0x100
	s_addc_u32 s83, s43, 0
	s_mov_b32 s42, 0
	s_add_i32 s72, s42, 2
	s_add_u32 s73, vcc_lo, 0x80
	s_addc_u32 s43, vcc_hi, 0
	s_add_i32 s45, 0, 0x10000
	s_cmp_eq_u32 s63, s42
	s_cselect_b32 s43, s9, s43
	s_cselect_b32 s42, s8, s73
	v_add_u32_e32 v140, s45, v143
	s_cselect_b32 s75, s91, s83
	s_cselect_b32 s74, s90, s82
	s_add_i32 s73, 0, 0x14000
	ds_read_b128 v[146:149], v140
	ds_read_b128 v[150:153], v140 offset:1024
	ds_read_b128 v[154:157], v140 offset:2048
	ds_read_b128 v[158:161], v140 offset:3072
	v_add_u32_e32 v140, s73, v143
	ds_read_b128 v[162:165], v140
	ds_read_b128 v[166:169], v140 offset:1024
	ds_read_b128 v[170:173], v140 offset:2048
	ds_read_b128 v[174:177], v140 offset:3072
	v_lshl_add_u64 v[140:141], vcc, 0, v[136:137]
	s_add_i32 m0, s59, 0xc000
	ds_read_b128 v[178:181], v145
	ds_read_b128 v[182:185], v145 offset:1024
	ds_read_b128 v[186:189], v145 offset:2048
	ds_read_b128 v[190:193], v145 offset:3072
	ds_read_b128 v[202:205], v145 offset:4096
	ds_read_b128 v[206:209], v145 offset:5120
	ds_read_b128 v[220:223], v145 offset:6144
	ds_read_b128 v[224:227], v145 offset:7168
	global_load_lds_dwordx4 v[140:141], off
	v_lshl_add_u64 v[140:141], vcc, 0, v[138:139]
	s_add_i32 m0, s59, 0xe000
	s_nop 0
	global_load_lds_dwordx4 v[140:141], off
	s_waitcnt vmcnt(8)
	s_waitcnt lgkmcnt(0)
	s_barrier
	s_setprio 1
	s_waitcnt lgkmcnt(0)
	v_mfma_f32_16x16x32_bf16 v[126:129], v[146:149], v[178:181], 0
	v_mfma_f32_16x16x32_bf16 v[122:125], v[154:157], v[178:181], 0
	v_mfma_f32_16x16x32_bf16 v[118:121], v[146:149], v[186:189], 0
	v_mfma_f32_16x16x32_bf16 v[110:113], v[154:157], v[186:189], 0
	v_mfma_f32_16x16x32_bf16 v[102:105], v[146:149], v[202:205], 0
	v_mfma_f32_16x16x32_bf16 v[94:97], v[154:157], v[202:205], 0
	v_mfma_f32_16x16x32_bf16 v[86:89], v[146:149], v[220:223], 0
	v_mfma_f32_16x16x32_bf16 v[78:81], v[154:157], v[220:223], 0
	v_mfma_f32_16x16x32_bf16 v[126:129], v[150:153], v[182:185], v[126:129]
	v_mfma_f32_16x16x32_bf16 v[122:125], v[158:161], v[182:185], v[122:125]
	v_mfma_f32_16x16x32_bf16 v[118:121], v[150:153], v[190:193], v[118:121]
	v_mfma_f32_16x16x32_bf16 v[110:113], v[158:161], v[190:193], v[110:113]
	v_mfma_f32_16x16x32_bf16 v[102:105], v[150:153], v[206:209], v[102:105]
	v_mfma_f32_16x16x32_bf16 v[94:97], v[158:161], v[206:209], v[94:97]
	v_mfma_f32_16x16x32_bf16 v[86:89], v[150:153], v[224:227], v[86:89]
	v_mfma_f32_16x16x32_bf16 v[78:81], v[158:161], v[224:227], v[78:81]
	s_setprio 0
	s_setprio 1
	v_mfma_f32_16x16x32_bf16 v[114:117], v[162:165], v[178:181], 0
	v_mfma_f32_16x16x32_bf16 v[106:109], v[170:173], v[178:181], 0
	v_mfma_f32_16x16x32_bf16 v[98:101], v[162:165], v[186:189], 0
	v_mfma_f32_16x16x32_bf16 v[90:93], v[170:173], v[186:189], 0
	v_mfma_f32_16x16x32_bf16 v[82:85], v[162:165], v[202:205], 0
	v_mfma_f32_16x16x32_bf16 v[74:77], v[170:173], v[202:205], 0
	v_mfma_f32_16x16x32_bf16 v[70:73], v[162:165], v[220:223], 0
	v_mfma_f32_16x16x32_bf16 v[66:69], v[170:173], v[220:223], 0
	v_mfma_f32_16x16x32_bf16 v[114:117], v[166:169], v[182:185], v[114:117]
	v_mfma_f32_16x16x32_bf16 v[106:109], v[174:177], v[182:185], v[106:109]
	v_mfma_f32_16x16x32_bf16 v[98:101], v[166:169], v[190:193], v[98:101]
	v_mfma_f32_16x16x32_bf16 v[90:93], v[174:177], v[190:193], v[90:93]
	v_mfma_f32_16x16x32_bf16 v[82:85], v[166:169], v[206:209], v[82:85]
	v_mfma_f32_16x16x32_bf16 v[74:77], v[174:177], v[206:209], v[74:77]
	v_mfma_f32_16x16x32_bf16 v[70:73], v[166:169], v[224:227], v[70:73]
	v_mfma_f32_16x16x32_bf16 v[66:69], v[174:177], v[224:227], v[66:69]
	s_setprio 0
	s_barrier
	s_add_i32 s45, s45, s54
	v_lshl_add_u64 v[140:141], s[74:75], 0, v[0:1]
	s_mov_b32 m0, s45
	ds_read_b128 v[178:181], v145 offset:16384
	ds_read_b128 v[182:185], v145 offset:17408
	ds_read_b128 v[186:189], v145 offset:18432
	ds_read_b128 v[190:193], v145 offset:19456
	ds_read_b128 v[202:205], v145 offset:20480
	ds_read_b128 v[206:209], v145 offset:21504
	ds_read_b128 v[220:223], v145 offset:22528
	ds_read_b128 v[224:227], v145 offset:23552
	global_load_lds_dwordx4 v[140:141], off
	s_add_i32 m0, s45, 0x2000
	v_lshl_add_u64 v[194:195], s[74:75], 0, v[134:135]
	s_add_u32 s74, s74, s80
	s_addc_u32 s75, s75, 0
	s_add_i32 s45, s73, s54
	global_load_lds_dwordx4 v[194:195], off
	v_lshl_add_u64 v[198:199], s[74:75], 0, v[0:1]
	s_mov_b32 m0, s45
	v_lshl_add_u64 v[200:201], s[74:75], 0, v[134:135]
	global_load_lds_dwordx4 v[198:199], off
	s_add_i32 m0, s45, 0x2000
	v_lshl_add_u64 v[210:211], s[42:43], 0, v[130:131]
	global_load_lds_dwordx4 v[200:201], off
	s_mov_b32 m0, s59
	v_lshl_add_u64 v[212:213], s[42:43], 0, v[132:133]
	global_load_lds_dwordx4 v[210:211], off
	s_mov_b32 m0, s60
	s_nop 0
	global_load_lds_dwordx4 v[212:213], off
	s_waitcnt vmcnt(8)
	s_waitcnt lgkmcnt(0)
	s_barrier
	s_setprio 1
	s_waitcnt lgkmcnt(0)
	v_mfma_f32_16x16x32_bf16 v[62:65], v[146:149], v[178:181], 0
	v_mfma_f32_16x16x32_bf16 v[58:61], v[154:157], v[178:181], 0
	v_mfma_f32_16x16x32_bf16 v[54:57], v[146:149], v[186:189], 0
	v_mfma_f32_16x16x32_bf16 v[46:49], v[154:157], v[186:189], 0
	v_mfma_f32_16x16x32_bf16 v[38:41], v[146:149], v[202:205], 0
	v_mfma_f32_16x16x32_bf16 v[30:33], v[154:157], v[202:205], 0
	v_mfma_f32_16x16x32_bf16 v[22:25], v[146:149], v[220:223], 0
	v_mfma_f32_16x16x32_bf16 v[14:17], v[154:157], v[220:223], 0
	v_mfma_f32_16x16x32_bf16 v[62:65], v[150:153], v[182:185], v[62:65]
	v_mfma_f32_16x16x32_bf16 v[58:61], v[158:161], v[182:185], v[58:61]
	v_mfma_f32_16x16x32_bf16 v[54:57], v[150:153], v[190:193], v[54:57]
	v_mfma_f32_16x16x32_bf16 v[46:49], v[158:161], v[190:193], v[46:49]
	v_mfma_f32_16x16x32_bf16 v[38:41], v[150:153], v[206:209], v[38:41]
	v_mfma_f32_16x16x32_bf16 v[30:33], v[158:161], v[206:209], v[30:33]
	v_mfma_f32_16x16x32_bf16 v[22:25], v[150:153], v[224:227], v[22:25]
	v_mfma_f32_16x16x32_bf16 v[14:17], v[158:161], v[224:227], v[14:17]
	s_setprio 0
	s_setprio 1
	v_mfma_f32_16x16x32_bf16 v[50:53], v[162:165], v[178:181], 0
	v_mfma_f32_16x16x32_bf16 v[42:45], v[170:173], v[178:181], 0
	v_mfma_f32_16x16x32_bf16 v[34:37], v[162:165], v[186:189], 0
	v_mfma_f32_16x16x32_bf16 v[26:29], v[170:173], v[186:189], 0
	v_mfma_f32_16x16x32_bf16 v[18:21], v[162:165], v[202:205], 0
	v_mfma_f32_16x16x32_bf16 v[10:13], v[170:173], v[202:205], 0
	v_mfma_f32_16x16x32_bf16 v[6:9], v[162:165], v[220:223], 0
	v_mfma_f32_16x16x32_bf16 v[2:5], v[170:173], v[220:223], 0
	v_mfma_f32_16x16x32_bf16 v[50:53], v[166:169], v[182:185], v[50:53]
	v_mfma_f32_16x16x32_bf16 v[42:45], v[174:177], v[182:185], v[42:45]
	v_mfma_f32_16x16x32_bf16 v[34:37], v[166:169], v[190:193], v[34:37]
	v_mfma_f32_16x16x32_bf16 v[26:29], v[174:177], v[190:193], v[26:29]
	v_mfma_f32_16x16x32_bf16 v[18:21], v[166:169], v[206:209], v[18:21]
	v_mfma_f32_16x16x32_bf16 v[10:13], v[174:177], v[206:209], v[10:13]
	v_mfma_f32_16x16x32_bf16 v[6:9], v[166:169], v[224:227], v[6:9]
	v_mfma_f32_16x16x32_bf16 v[2:5], v[174:177], v[224:227], v[2:5]
	s_setprio 0
	s_barrier
	s_add_i32 s45, 0, 0x18000
	s_add_i32 s73, 0, 0x1c000
	v_add_u32_e32 v158, s45, v143
	v_add_u32_e32 v174, s73, v143
	ds_read_b128 v[146:149], v158
	ds_read_b128 v[150:153], v158 offset:1024
	ds_read_b128 v[154:157], v158 offset:2048
	ds_read_b128 v[158:161], v158 offset:3072
	ds_read_b128 v[162:165], v174
	ds_read_b128 v[166:169], v174 offset:1024
	ds_read_b128 v[170:173], v174 offset:2048
	ds_read_b128 v[174:177], v174 offset:3072
	s_add_u32 s42, s42, s80
	s_addc_u32 s43, s43, 0
	s_mov_b32 m0, s61
	v_lshl_add_u64 v[214:215], s[42:43], 0, v[130:131]
	ds_read_b128 v[178:181], v145 offset:32768
	ds_read_b128 v[182:185], v145 offset:33792
	ds_read_b128 v[186:189], v145 offset:34816
	ds_read_b128 v[190:193], v145 offset:35840
	ds_read_b128 v[202:205], v145 offset:36864
	ds_read_b128 v[206:209], v145 offset:37888
	ds_read_b128 v[220:223], v145 offset:38912
	ds_read_b128 v[224:227], v145 offset:39936
	global_load_lds_dwordx4 v[214:215], off
	v_lshl_add_u64 v[214:215], s[42:43], 0, v[132:133]
	s_mov_b32 m0, s62
	s_nop 0
	global_load_lds_dwordx4 v[214:215], off
	s_waitcnt vmcnt(8)
	s_waitcnt lgkmcnt(0)
	s_barrier
	s_setprio 1
	s_waitcnt lgkmcnt(0)
	v_mfma_f32_16x16x32_bf16 v[126:129], v[146:149], v[178:181], v[126:129]
	v_mfma_f32_16x16x32_bf16 v[122:125], v[154:157], v[178:181], v[122:125]
	v_mfma_f32_16x16x32_bf16 v[118:121], v[146:149], v[186:189], v[118:121]
	v_mfma_f32_16x16x32_bf16 v[110:113], v[154:157], v[186:189], v[110:113]
	v_mfma_f32_16x16x32_bf16 v[102:105], v[146:149], v[202:205], v[102:105]
	v_mfma_f32_16x16x32_bf16 v[94:97], v[154:157], v[202:205], v[94:97]
	v_mfma_f32_16x16x32_bf16 v[86:89], v[146:149], v[220:223], v[86:89]
	v_mfma_f32_16x16x32_bf16 v[78:81], v[154:157], v[220:223], v[78:81]
	v_mfma_f32_16x16x32_bf16 v[126:129], v[150:153], v[182:185], v[126:129]
	v_mfma_f32_16x16x32_bf16 v[122:125], v[158:161], v[182:185], v[122:125]
	v_mfma_f32_16x16x32_bf16 v[118:121], v[150:153], v[190:193], v[118:121]
	v_mfma_f32_16x16x32_bf16 v[110:113], v[158:161], v[190:193], v[110:113]
	v_mfma_f32_16x16x32_bf16 v[102:105], v[150:153], v[206:209], v[102:105]
	v_mfma_f32_16x16x32_bf16 v[94:97], v[158:161], v[206:209], v[94:97]
	v_mfma_f32_16x16x32_bf16 v[86:89], v[150:153], v[224:227], v[86:89]
	v_mfma_f32_16x16x32_bf16 v[78:81], v[158:161], v[224:227], v[78:81]
	s_setprio 0
	s_setprio 1
	v_mfma_f32_16x16x32_bf16 v[114:117], v[162:165], v[178:181], v[114:117]
	v_mfma_f32_16x16x32_bf16 v[106:109], v[170:173], v[178:181], v[106:109]
	v_mfma_f32_16x16x32_bf16 v[98:101], v[162:165], v[186:189], v[98:101]
	v_mfma_f32_16x16x32_bf16 v[90:93], v[170:173], v[186:189], v[90:93]
	v_mfma_f32_16x16x32_bf16 v[82:85], v[162:165], v[202:205], v[82:85]
	v_mfma_f32_16x16x32_bf16 v[74:77], v[170:173], v[202:205], v[74:77]
	v_mfma_f32_16x16x32_bf16 v[70:73], v[162:165], v[220:223], v[70:73]
	v_mfma_f32_16x16x32_bf16 v[66:69], v[170:173], v[220:223], v[66:69]
	v_mfma_f32_16x16x32_bf16 v[114:117], v[166:169], v[182:185], v[114:117]
	v_mfma_f32_16x16x32_bf16 v[106:109], v[174:177], v[182:185], v[106:109]
	v_mfma_f32_16x16x32_bf16 v[98:101], v[166:169], v[190:193], v[98:101]
	v_mfma_f32_16x16x32_bf16 v[90:93], v[174:177], v[190:193], v[90:93]
	v_mfma_f32_16x16x32_bf16 v[82:85], v[166:169], v[206:209], v[82:85]
	v_mfma_f32_16x16x32_bf16 v[74:77], v[174:177], v[206:209], v[74:77]
	v_mfma_f32_16x16x32_bf16 v[70:73], v[166:169], v[224:227], v[70:73]
	v_mfma_f32_16x16x32_bf16 v[66:69], v[174:177], v[224:227], v[66:69]
	s_setprio 0
	s_barrier
	s_add_i32 s42, s45, s54
	v_lshl_add_u64 v[140:141], v[140:141], 0, s[84:85]
	s_mov_b32 m0, s42
	ds_read_b128 v[178:181], v145 offset:49152
	ds_read_b128 v[182:185], v145 offset:50176
	ds_read_b128 v[186:189], v145 offset:51200
	ds_read_b128 v[190:193], v145 offset:52224
	ds_read_b128 v[202:205], v145 offset:53248
	ds_read_b128 v[206:209], v145 offset:54272
	ds_read_b128 v[220:223], v145 offset:55296
	ds_read_b128 v[224:227], v145 offset:56320
	global_load_lds_dwordx4 v[140:141], off
	v_lshl_add_u64 v[140:141], v[194:195], 0, s[84:85]
	s_add_i32 m0, s42, 0x2000
	s_add_i32 s42, s73, s54
	global_load_lds_dwordx4 v[140:141], off
	v_lshl_add_u64 v[140:141], v[198:199], 0, s[84:85]
	s_mov_b32 m0, s42
	s_nop 0
	global_load_lds_dwordx4 v[140:141], off
	v_lshl_add_u64 v[140:141], v[200:201], 0, s[84:85]
	s_add_i32 m0, s42, 0x2000
	s_nop 0
	global_load_lds_dwordx4 v[140:141], off
	v_lshl_add_u64 v[140:141], v[210:211], 0, s[84:85]
	s_mov_b32 m0, s64
	s_nop 0
	global_load_lds_dwordx4 v[140:141], off
	v_lshl_add_u64 v[140:141], v[212:213], 0, s[84:85]
	s_mov_b32 m0, s65
	s_nop 0
	global_load_lds_dwordx4 v[140:141], off
	s_waitcnt vmcnt(8)
	s_waitcnt lgkmcnt(0)
	s_barrier
	s_setprio 1
	s_waitcnt lgkmcnt(0)
	v_mfma_f32_16x16x32_bf16 v[62:65], v[146:149], v[178:181], v[62:65]
	v_mfma_f32_16x16x32_bf16 v[58:61], v[154:157], v[178:181], v[58:61]
	v_mfma_f32_16x16x32_bf16 v[54:57], v[146:149], v[186:189], v[54:57]
	v_mfma_f32_16x16x32_bf16 v[46:49], v[154:157], v[186:189], v[46:49]
	v_mfma_f32_16x16x32_bf16 v[38:41], v[146:149], v[202:205], v[38:41]
	v_mfma_f32_16x16x32_bf16 v[30:33], v[154:157], v[202:205], v[30:33]
	v_mfma_f32_16x16x32_bf16 v[22:25], v[146:149], v[220:223], v[22:25]
	v_mfma_f32_16x16x32_bf16 v[14:17], v[154:157], v[220:223], v[14:17]
	v_mfma_f32_16x16x32_bf16 v[62:65], v[150:153], v[182:185], v[62:65]
	v_mfma_f32_16x16x32_bf16 v[58:61], v[158:161], v[182:185], v[58:61]
	v_mfma_f32_16x16x32_bf16 v[54:57], v[150:153], v[190:193], v[54:57]
	v_mfma_f32_16x16x32_bf16 v[46:49], v[158:161], v[190:193], v[46:49]
	v_mfma_f32_16x16x32_bf16 v[38:41], v[150:153], v[206:209], v[38:41]
	v_mfma_f32_16x16x32_bf16 v[30:33], v[158:161], v[206:209], v[30:33]
	v_mfma_f32_16x16x32_bf16 v[22:25], v[150:153], v[224:227], v[22:25]
	v_mfma_f32_16x16x32_bf16 v[14:17], v[158:161], v[224:227], v[14:17]
	s_setprio 0
	s_setprio 1
	v_mfma_f32_16x16x32_bf16 v[50:53], v[162:165], v[178:181], v[50:53]
	v_mfma_f32_16x16x32_bf16 v[42:45], v[170:173], v[178:181], v[42:45]
	v_mfma_f32_16x16x32_bf16 v[34:37], v[162:165], v[186:189], v[34:37]
	v_mfma_f32_16x16x32_bf16 v[26:29], v[170:173], v[186:189], v[26:29]
	v_mfma_f32_16x16x32_bf16 v[18:21], v[162:165], v[202:205], v[18:21]
	v_mfma_f32_16x16x32_bf16 v[10:13], v[170:173], v[202:205], v[10:13]
	v_mfma_f32_16x16x32_bf16 v[6:9], v[162:165], v[220:223], v[6:9]
	v_mfma_f32_16x16x32_bf16 v[2:5], v[170:173], v[220:223], v[2:5]
	v_mfma_f32_16x16x32_bf16 v[50:53], v[166:169], v[182:185], v[50:53]
	v_mfma_f32_16x16x32_bf16 v[42:45], v[174:177], v[182:185], v[42:45]
	v_mfma_f32_16x16x32_bf16 v[34:37], v[166:169], v[190:193], v[34:37]
	v_mfma_f32_16x16x32_bf16 v[26:29], v[174:177], v[190:193], v[26:29]
	v_mfma_f32_16x16x32_bf16 v[18:21], v[166:169], v[206:209], v[18:21]
	v_mfma_f32_16x16x32_bf16 v[10:13], v[174:177], v[206:209], v[10:13]
	v_mfma_f32_16x16x32_bf16 v[6:9], v[166:169], v[224:227], v[6:9]
	v_mfma_f32_16x16x32_bf16 v[2:5], v[174:177], v[224:227], v[2:5]
	s_setprio 0
	s_barrier
	s_add_u32 vcc_lo, vcc_lo, 0x100
	s_addc_u32 vcc_hi, vcc_hi, 0
	s_add_u32 s82, s82, 0x100
	s_addc_u32 s83, s83, 0
	s_cmp_ge_u32 s72, s66
	s_mov_b32 s42, s72
	s_cbranch_scc1 .Lpeel_exit_bf
	.p2alignl 6, 3212836864

.LBB0_351:
	s_add_u32 s8, s76, 0x80
	s_addc_u32 s9, s77, 0
	s_add_u32 s59, s36, 0x100
	s_addc_u32 s60, s37, 0
	s_mov_b32 s36, 0
	s_add_i32 s61, s36, 2
	s_add_u32 s45, s8, 0x80
	s_addc_u32 s37, s9, 0
	s_add_i32 s64, 0, 0x10000
	s_cmp_eq_u32 s48, s36
	s_cselect_b32 s37, s39, s37
	s_cselect_b32 s36, s38, s45
	s_cselect_b32 s63, s41, s60
	s_cselect_b32 s62, s40, s59
	s_add_i32 s45, 0, 0x14000
	v_add_u32_e32 v158, s64, v148
	v_add_u32_e32 v174, s45, v148
	ds_read_b128 v[144:147], v158
	ds_read_b128 v[150:153], v158 offset:1024
	ds_read_b128 v[154:157], v158 offset:2048
	ds_read_b128 v[158:161], v158 offset:3072
	ds_read_b128 v[162:165], v174
	ds_read_b128 v[166:169], v174 offset:1024
	ds_read_b128 v[170:173], v174 offset:2048
	ds_read_b128 v[174:177], v174 offset:3072
	v_lshl_add_u64 v[194:195], s[8:9], 0, v[140:141]
	s_add_i32 m0, s82, 0xc000
	ds_read_b128 v[178:181], v149
	ds_read_b128 v[182:185], v149 offset:1024
	ds_read_b128 v[186:189], v149 offset:2048
	ds_read_b128 v[190:193], v149 offset:3072
	ds_read_b128 v[202:205], v149 offset:4096
	ds_read_b128 v[206:209], v149 offset:5120
	ds_read_b128 v[220:223], v149 offset:6144
	ds_read_b128 v[224:227], v149 offset:7168
	global_load_lds_dwordx4 v[194:195], off
	v_lshl_add_u64 v[194:195], s[8:9], 0, v[142:143]
	s_add_i32 m0, s82, 0xe000
	s_nop 0
	global_load_lds_dwordx4 v[194:195], off
	s_waitcnt vmcnt(8)
	s_waitcnt lgkmcnt(0)
	s_barrier
	s_setprio 1
	s_waitcnt lgkmcnt(0)
	v_mfma_f32_16x16x32_bf16 v[126:129], v[144:147], v[178:181], 0
	v_mfma_f32_16x16x32_bf16 v[122:125], v[154:157], v[178:181], 0
	v_mfma_f32_16x16x32_bf16 v[110:113], v[144:147], v[186:189], 0
	v_mfma_f32_16x16x32_bf16 v[106:109], v[154:157], v[186:189], 0
	v_mfma_f32_16x16x32_bf16 v[94:97], v[144:147], v[202:205], 0
	v_mfma_f32_16x16x32_bf16 v[90:93], v[154:157], v[202:205], 0
	v_mfma_f32_16x16x32_bf16 v[78:81], v[144:147], v[220:223], 0
	v_mfma_f32_16x16x32_bf16 v[74:77], v[154:157], v[220:223], 0
	v_mfma_f32_16x16x32_bf16 v[126:129], v[150:153], v[182:185], v[126:129]
	v_mfma_f32_16x16x32_bf16 v[122:125], v[158:161], v[182:185], v[122:125]
	v_mfma_f32_16x16x32_bf16 v[110:113], v[150:153], v[190:193], v[110:113]
	v_mfma_f32_16x16x32_bf16 v[106:109], v[158:161], v[190:193], v[106:109]
	v_mfma_f32_16x16x32_bf16 v[94:97], v[150:153], v[206:209], v[94:97]
	v_mfma_f32_16x16x32_bf16 v[90:93], v[158:161], v[206:209], v[90:93]
	v_mfma_f32_16x16x32_bf16 v[78:81], v[150:153], v[224:227], v[78:81]
	v_mfma_f32_16x16x32_bf16 v[74:77], v[158:161], v[224:227], v[74:77]
	s_setprio 0
	s_setprio 1
	v_mfma_f32_16x16x32_bf16 v[118:121], v[162:165], v[178:181], 0
	v_mfma_f32_16x16x32_bf16 v[114:117], v[170:173], v[178:181], 0
	v_mfma_f32_16x16x32_bf16 v[102:105], v[162:165], v[186:189], 0
	v_mfma_f32_16x16x32_bf16 v[98:101], v[170:173], v[186:189], 0
	v_mfma_f32_16x16x32_bf16 v[86:89], v[162:165], v[202:205], 0
	v_mfma_f32_16x16x32_bf16 v[82:85], v[170:173], v[202:205], 0
	v_mfma_f32_16x16x32_bf16 v[70:73], v[162:165], v[220:223], 0
	v_mfma_f32_16x16x32_bf16 v[66:69], v[170:173], v[220:223], 0
	v_mfma_f32_16x16x32_bf16 v[118:121], v[166:169], v[182:185], v[118:121]
	v_mfma_f32_16x16x32_bf16 v[114:117], v[174:177], v[182:185], v[114:117]
	v_mfma_f32_16x16x32_bf16 v[102:105], v[166:169], v[190:193], v[102:105]
	v_mfma_f32_16x16x32_bf16 v[98:101], v[174:177], v[190:193], v[98:101]
	v_mfma_f32_16x16x32_bf16 v[86:89], v[166:169], v[206:209], v[86:89]
	v_mfma_f32_16x16x32_bf16 v[82:85], v[174:177], v[206:209], v[82:85]
	v_mfma_f32_16x16x32_bf16 v[70:73], v[166:169], v[224:227], v[70:73]
	v_mfma_f32_16x16x32_bf16 v[66:69], v[174:177], v[224:227], v[66:69]
	s_setprio 0
	s_barrier
	s_add_i32 s64, s64, s79
	v_lshl_add_u64 v[194:195], s[62:63], 0, v[132:133]
	s_mov_b32 m0, s64
	ds_read_b128 v[178:181], v149 offset:16384
	ds_read_b128 v[182:185], v149 offset:17408
	ds_read_b128 v[186:189], v149 offset:18432
	ds_read_b128 v[190:193], v149 offset:19456
	ds_read_b128 v[202:205], v149 offset:20480
	ds_read_b128 v[206:209], v149 offset:21504
	ds_read_b128 v[220:223], v149 offset:22528
	ds_read_b128 v[224:227], v149 offset:23552
	global_load_lds_dwordx4 v[194:195], off
	s_add_i32 m0, s64, 0x2000
	v_lshl_add_u64 v[198:199], s[62:63], 0, v[136:137]
	s_add_u32 s62, s62, s80
	s_addc_u32 s63, s63, 0
	s_add_i32 s45, s45, s79
	global_load_lds_dwordx4 v[198:199], off
	v_lshl_add_u64 v[200:201], s[62:63], 0, v[132:133]
	s_mov_b32 m0, s45
	v_lshl_add_u64 v[210:211], s[62:63], 0, v[136:137]
	global_load_lds_dwordx4 v[200:201], off
	s_add_i32 m0, s45, 0x2000
	v_lshl_add_u64 v[212:213], s[36:37], 0, v[130:131]
	global_load_lds_dwordx4 v[210:211], off
	s_mov_b32 m0, s82
	v_lshl_add_u64 v[214:215], s[36:37], 0, v[134:135]
	global_load_lds_dwordx4 v[212:213], off
	s_mov_b32 m0, s83
	s_nop 0
	global_load_lds_dwordx4 v[214:215], off
	s_waitcnt vmcnt(8)
	s_waitcnt lgkmcnt(0)
	s_barrier
	s_setprio 1
	s_waitcnt lgkmcnt(0)
	v_mfma_f32_16x16x32_bf16 v[62:65], v[144:147], v[178:181], 0
	v_mfma_f32_16x16x32_bf16 v[58:61], v[154:157], v[178:181], 0
	v_mfma_f32_16x16x32_bf16 v[46:49], v[144:147], v[186:189], 0
	v_mfma_f32_16x16x32_bf16 v[42:45], v[154:157], v[186:189], 0
	v_mfma_f32_16x16x32_bf16 v[30:33], v[144:147], v[202:205], 0
	v_mfma_f32_16x16x32_bf16 v[26:29], v[154:157], v[202:205], 0
	v_mfma_f32_16x16x32_bf16 v[14:17], v[144:147], v[220:223], 0
	v_mfma_f32_16x16x32_bf16 v[10:13], v[154:157], v[220:223], 0
	v_mfma_f32_16x16x32_bf16 v[62:65], v[150:153], v[182:185], v[62:65]
	v_mfma_f32_16x16x32_bf16 v[58:61], v[158:161], v[182:185], v[58:61]
	v_mfma_f32_16x16x32_bf16 v[46:49], v[150:153], v[190:193], v[46:49]
	v_mfma_f32_16x16x32_bf16 v[42:45], v[158:161], v[190:193], v[42:45]
	v_mfma_f32_16x16x32_bf16 v[30:33], v[150:153], v[206:209], v[30:33]
	v_mfma_f32_16x16x32_bf16 v[26:29], v[158:161], v[206:209], v[26:29]
	v_mfma_f32_16x16x32_bf16 v[14:17], v[150:153], v[224:227], v[14:17]
	v_mfma_f32_16x16x32_bf16 v[10:13], v[158:161], v[224:227], v[10:13]
	s_setprio 0
	s_setprio 1
	v_mfma_f32_16x16x32_bf16 v[54:57], v[162:165], v[178:181], 0
	v_mfma_f32_16x16x32_bf16 v[50:53], v[170:173], v[178:181], 0
	v_mfma_f32_16x16x32_bf16 v[38:41], v[162:165], v[186:189], 0
	v_mfma_f32_16x16x32_bf16 v[34:37], v[170:173], v[186:189], 0
	v_mfma_f32_16x16x32_bf16 v[22:25], v[162:165], v[202:205], 0
	v_mfma_f32_16x16x32_bf16 v[18:21], v[170:173], v[202:205], 0
	v_mfma_f32_16x16x32_bf16 v[6:9], v[162:165], v[220:223], 0
	v_mfma_f32_16x16x32_bf16 v[2:5], v[170:173], v[220:223], 0
	v_mfma_f32_16x16x32_bf16 v[54:57], v[166:169], v[182:185], v[54:57]
	v_mfma_f32_16x16x32_bf16 v[50:53], v[174:177], v[182:185], v[50:53]
	v_mfma_f32_16x16x32_bf16 v[38:41], v[166:169], v[190:193], v[38:41]
	v_mfma_f32_16x16x32_bf16 v[34:37], v[174:177], v[190:193], v[34:37]
	v_mfma_f32_16x16x32_bf16 v[22:25], v[166:169], v[206:209], v[22:25]
	v_mfma_f32_16x16x32_bf16 v[18:21], v[174:177], v[206:209], v[18:21]
	v_mfma_f32_16x16x32_bf16 v[6:9], v[166:169], v[224:227], v[6:9]
	v_mfma_f32_16x16x32_bf16 v[2:5], v[174:177], v[224:227], v[2:5]
	s_setprio 0
	s_barrier
	s_add_i32 s45, 0, 0x18000
	s_add_i32 s62, 0, 0x1c000
	v_add_u32_e32 v158, s45, v148
	v_add_u32_e32 v174, s62, v148
	ds_read_b128 v[144:147], v158
	ds_read_b128 v[150:153], v158 offset:1024
	ds_read_b128 v[154:157], v158 offset:2048
	ds_read_b128 v[158:161], v158 offset:3072
	ds_read_b128 v[162:165], v174
	ds_read_b128 v[166:169], v174 offset:1024
	ds_read_b128 v[170:173], v174 offset:2048
	ds_read_b128 v[174:177], v174 offset:3072
	s_add_u32 s36, s36, s80
	s_addc_u32 s37, s37, 0
	s_mov_b32 m0, s86
	v_lshl_add_u64 v[216:217], s[36:37], 0, v[130:131]
	ds_read_b128 v[178:181], v149 offset:32768
	ds_read_b128 v[182:185], v149 offset:33792
	ds_read_b128 v[186:189], v149 offset:34816
	ds_read_b128 v[190:193], v149 offset:35840
	ds_read_b128 v[202:205], v149 offset:36864
	ds_read_b128 v[206:209], v149 offset:37888
	ds_read_b128 v[220:223], v149 offset:38912
	ds_read_b128 v[224:227], v149 offset:39936
	global_load_lds_dwordx4 v[216:217], off
	v_lshl_add_u64 v[216:217], s[36:37], 0, v[134:135]
	s_mov_b32 m0, s87
	s_nop 0
	global_load_lds_dwordx4 v[216:217], off
	s_waitcnt vmcnt(8)
	s_waitcnt lgkmcnt(0)
	s_barrier
	s_setprio 1
	s_waitcnt lgkmcnt(0)
	v_mfma_f32_16x16x32_bf16 v[126:129], v[144:147], v[178:181], v[126:129]
	v_mfma_f32_16x16x32_bf16 v[122:125], v[154:157], v[178:181], v[122:125]
	v_mfma_f32_16x16x32_bf16 v[110:113], v[144:147], v[186:189], v[110:113]
	v_mfma_f32_16x16x32_bf16 v[106:109], v[154:157], v[186:189], v[106:109]
	v_mfma_f32_16x16x32_bf16 v[94:97], v[144:147], v[202:205], v[94:97]
	v_mfma_f32_16x16x32_bf16 v[90:93], v[154:157], v[202:205], v[90:93]
	v_mfma_f32_16x16x32_bf16 v[78:81], v[144:147], v[220:223], v[78:81]
	v_mfma_f32_16x16x32_bf16 v[74:77], v[154:157], v[220:223], v[74:77]
	v_mfma_f32_16x16x32_bf16 v[126:129], v[150:153], v[182:185], v[126:129]
	v_mfma_f32_16x16x32_bf16 v[122:125], v[158:161], v[182:185], v[122:125]
	v_mfma_f32_16x16x32_bf16 v[110:113], v[150:153], v[190:193], v[110:113]
	v_mfma_f32_16x16x32_bf16 v[106:109], v[158:161], v[190:193], v[106:109]
	v_mfma_f32_16x16x32_bf16 v[94:97], v[150:153], v[206:209], v[94:97]
	v_mfma_f32_16x16x32_bf16 v[90:93], v[158:161], v[206:209], v[90:93]
	v_mfma_f32_16x16x32_bf16 v[78:81], v[150:153], v[224:227], v[78:81]
	v_mfma_f32_16x16x32_bf16 v[74:77], v[158:161], v[224:227], v[74:77]
	s_setprio 0
	s_setprio 1
	v_mfma_f32_16x16x32_bf16 v[118:121], v[162:165], v[178:181], v[118:121]
	v_mfma_f32_16x16x32_bf16 v[114:117], v[170:173], v[178:181], v[114:117]
	v_mfma_f32_16x16x32_bf16 v[102:105], v[162:165], v[186:189], v[102:105]
	v_mfma_f32_16x16x32_bf16 v[98:101], v[170:173], v[186:189], v[98:101]
	v_mfma_f32_16x16x32_bf16 v[86:89], v[162:165], v[202:205], v[86:89]
	v_mfma_f32_16x16x32_bf16 v[82:85], v[170:173], v[202:205], v[82:85]
	v_mfma_f32_16x16x32_bf16 v[70:73], v[162:165], v[220:223], v[70:73]
	v_mfma_f32_16x16x32_bf16 v[66:69], v[170:173], v[220:223], v[66:69]
	v_mfma_f32_16x16x32_bf16 v[118:121], v[166:169], v[182:185], v[118:121]
	v_mfma_f32_16x16x32_bf16 v[114:117], v[174:177], v[182:185], v[114:117]
	v_mfma_f32_16x16x32_bf16 v[102:105], v[166:169], v[190:193], v[102:105]
	v_mfma_f32_16x16x32_bf16 v[98:101], v[174:177], v[190:193], v[98:101]
	v_mfma_f32_16x16x32_bf16 v[86:89], v[166:169], v[206:209], v[86:89]
	v_mfma_f32_16x16x32_bf16 v[82:85], v[174:177], v[206:209], v[82:85]
	v_mfma_f32_16x16x32_bf16 v[70:73], v[166:169], v[224:227], v[70:73]
	v_mfma_f32_16x16x32_bf16 v[66:69], v[174:177], v[224:227], v[66:69]
	s_setprio 0
	s_barrier
	s_add_i32 s36, s45, s79
	v_lshl_add_u64 v[194:195], v[194:195], 0, s[84:85]
	s_mov_b32 m0, s36
	ds_read_b128 v[178:181], v149 offset:49152
	ds_read_b128 v[182:185], v149 offset:50176
	ds_read_b128 v[186:189], v149 offset:51200
	ds_read_b128 v[190:193], v149 offset:52224
	ds_read_b128 v[202:205], v149 offset:53248
	ds_read_b128 v[206:209], v149 offset:54272
	ds_read_b128 v[220:223], v149 offset:55296
	ds_read_b128 v[224:227], v149 offset:56320
	global_load_lds_dwordx4 v[194:195], off
	v_lshl_add_u64 v[194:195], v[198:199], 0, s[84:85]
	s_add_i32 m0, s36, 0x2000
	s_add_i32 s36, s62, s79
	global_load_lds_dwordx4 v[194:195], off
	v_lshl_add_u64 v[194:195], v[200:201], 0, s[84:85]
	s_mov_b32 m0, s36
	s_nop 0
	global_load_lds_dwordx4 v[194:195], off
	v_lshl_add_u64 v[194:195], v[210:211], 0, s[84:85]
	s_add_i32 m0, s36, 0x2000
	s_nop 0
	global_load_lds_dwordx4 v[194:195], off
	v_lshl_add_u64 v[194:195], v[212:213], 0, s[84:85]
	s_mov_b32 m0, s46
	s_nop 0
	global_load_lds_dwordx4 v[194:195], off
	v_lshl_add_u64 v[194:195], v[214:215], 0, s[84:85]
	s_mov_b32 m0, s47
	s_nop 0
	global_load_lds_dwordx4 v[194:195], off
	s_waitcnt vmcnt(8)
	s_waitcnt lgkmcnt(0)
	s_barrier
	s_setprio 1
	s_waitcnt lgkmcnt(0)
	v_mfma_f32_16x16x32_bf16 v[62:65], v[144:147], v[178:181], v[62:65]
	v_mfma_f32_16x16x32_bf16 v[58:61], v[154:157], v[178:181], v[58:61]
	v_mfma_f32_16x16x32_bf16 v[46:49], v[144:147], v[186:189], v[46:49]
	v_mfma_f32_16x16x32_bf16 v[42:45], v[154:157], v[186:189], v[42:45]
	v_mfma_f32_16x16x32_bf16 v[30:33], v[144:147], v[202:205], v[30:33]
	v_mfma_f32_16x16x32_bf16 v[26:29], v[154:157], v[202:205], v[26:29]
	v_mfma_f32_16x16x32_bf16 v[14:17], v[144:147], v[220:223], v[14:17]
	v_mfma_f32_16x16x32_bf16 v[10:13], v[154:157], v[220:223], v[10:13]
	v_mfma_f32_16x16x32_bf16 v[62:65], v[150:153], v[182:185], v[62:65]
	v_mfma_f32_16x16x32_bf16 v[58:61], v[158:161], v[182:185], v[58:61]
	v_mfma_f32_16x16x32_bf16 v[46:49], v[150:153], v[190:193], v[46:49]
	v_mfma_f32_16x16x32_bf16 v[42:45], v[158:161], v[190:193], v[42:45]
	v_mfma_f32_16x16x32_bf16 v[30:33], v[150:153], v[206:209], v[30:33]
	v_mfma_f32_16x16x32_bf16 v[26:29], v[158:161], v[206:209], v[26:29]
	v_mfma_f32_16x16x32_bf16 v[14:17], v[150:153], v[224:227], v[14:17]
	v_mfma_f32_16x16x32_bf16 v[10:13], v[158:161], v[224:227], v[10:13]
	s_setprio 0
	s_setprio 1
	v_mfma_f32_16x16x32_bf16 v[54:57], v[162:165], v[178:181], v[54:57]
	v_mfma_f32_16x16x32_bf16 v[50:53], v[170:173], v[178:181], v[50:53]
	v_mfma_f32_16x16x32_bf16 v[38:41], v[162:165], v[186:189], v[38:41]
	v_mfma_f32_16x16x32_bf16 v[34:37], v[170:173], v[186:189], v[34:37]
	v_mfma_f32_16x16x32_bf16 v[22:25], v[162:165], v[202:205], v[22:25]
	v_mfma_f32_16x16x32_bf16 v[18:21], v[170:173], v[202:205], v[18:21]
	v_mfma_f32_16x16x32_bf16 v[6:9], v[162:165], v[220:223], v[6:9]
	v_mfma_f32_16x16x32_bf16 v[2:5], v[170:173], v[220:223], v[2:5]
	v_mfma_f32_16x16x32_bf16 v[54:57], v[166:169], v[182:185], v[54:57]
	v_mfma_f32_16x16x32_bf16 v[50:53], v[174:177], v[182:185], v[50:53]
	v_mfma_f32_16x16x32_bf16 v[38:41], v[166:169], v[190:193], v[38:41]
	v_mfma_f32_16x16x32_bf16 v[34:37], v[174:177], v[190:193], v[34:37]
	v_mfma_f32_16x16x32_bf16 v[22:25], v[166:169], v[206:209], v[22:25]
	v_mfma_f32_16x16x32_bf16 v[18:21], v[174:177], v[206:209], v[18:21]
	v_mfma_f32_16x16x32_bf16 v[6:9], v[166:169], v[224:227], v[6:9]
	v_mfma_f32_16x16x32_bf16 v[2:5], v[174:177], v[224:227], v[2:5]
	s_setprio 0
	s_barrier
	s_add_u32 s8, s8, 0x100
	s_addc_u32 s9, s9, 0
	s_add_u32 s59, s59, 0x100
	s_addc_u32 s60, s60, 0
	s_cmp_ge_u32 s61, s90
	s_mov_b32 s36, s61
	s_cbranch_scc1 .Lpeel_exit_vt
	.p2alignl 6, 3212836864

.LBB0_482:
	s_mov_b32 s38, 0
	s_mov_b64 s[36:37], 0x100
	v_mov_b64_e32 v[140:141], v[138:139]
	v_mov_b64_e32 v[142:143], v[136:137]
	.p2alignl 6, 3212836864

.LBB0_691:
	s_ashr_i32 s15, s14, 31
	s_lshl_b64 s[16:17], s[14:15], 19
	s_add_u32 s16, s82, s16
	s_addc_u32 s17, s83, s17
	s_and_b64 s[18:19], s[6:7], exec
	s_cselect_b32 s15, s17, s5
	s_cselect_b32 s46, s16, s4
	s_ashr_i32 s11, s10, 31
	s_lshl_b64 s[18:19], s[10:11], 19
	s_add_u32 s18, s34, s18
	s_addc_u32 s19, s35, s19
	s_and_b64 s[28:29], s[6:7], exec
	s_cselect_b32 s11, s19, s21
	s_cselect_b32 s47, s18, s20
	s_add_u32 s4, s4, 0x40080
	s_addc_u32 s5, s5, 0
	s_add_u32 s48, s20, 0x100
	s_addc_u32 s49, s21, 0
	s_mov_b32 s50, -2
	s_add_u32 s20, s4, 0xfffc0080
	s_addc_u32 s21, s5, -1
	s_add_i32 s51, 0, 0x10000
	s_cmp_eq_u32 s50, 12
	s_cselect_b32 s29, s15, s21
	s_cselect_b32 s28, s46, s20
	v_add_u32_e32 v140, s51, v143
	s_cselect_b32 s21, s11, s49
	s_cselect_b32 s20, s47, s48
	s_add_i32 s54, 0, 0x14000
	ds_read_b128 v[146:149], v140
	ds_read_b128 v[150:153], v140 offset:1024
	ds_read_b128 v[154:157], v140 offset:2048
	ds_read_b128 v[158:161], v140 offset:3072
	v_add_u32_e32 v140, s54, v143
	ds_read_b128 v[162:165], v140
	ds_read_b128 v[166:169], v140 offset:1024
	ds_read_b128 v[170:173], v140 offset:2048
	ds_read_b128 v[174:177], v140 offset:3072
	v_lshl_add_u64 v[140:141], s[4:5], 0, v[136:137]
	s_add_i32 m0, s38, 0xc000
	ds_read_b128 v[178:181], v145
	ds_read_b128 v[182:185], v145 offset:1024
	ds_read_b128 v[186:189], v145 offset:2048
	ds_read_b128 v[190:193], v145 offset:3072
	ds_read_b128 v[202:205], v145 offset:4096
	ds_read_b128 v[206:209], v145 offset:5120
	ds_read_b128 v[220:223], v145 offset:6144
	ds_read_b128 v[224:227], v145 offset:7168
	global_load_lds_dwordx4 v[140:141], off
	v_lshl_add_u64 v[140:141], s[4:5], 0, v[138:139]
	s_add_i32 m0, s38, 0xe000
	s_nop 0
	global_load_lds_dwordx4 v[140:141], off
	s_waitcnt vmcnt(8)
	s_waitcnt lgkmcnt(0)
	s_barrier
	s_setprio 1
	s_waitcnt lgkmcnt(0)
	v_mfma_f32_16x16x32_bf16 v[126:129], v[146:149], v[178:181], 0
	v_mfma_f32_16x16x32_bf16 v[118:121], v[154:157], v[178:181], 0
	v_mfma_f32_16x16x32_bf16 v[110:113], v[146:149], v[186:189], 0
	v_mfma_f32_16x16x32_bf16 v[102:105], v[154:157], v[186:189], 0
	v_mfma_f32_16x16x32_bf16 v[94:97], v[146:149], v[202:205], 0
	v_mfma_f32_16x16x32_bf16 v[86:89], v[154:157], v[202:205], 0
	v_mfma_f32_16x16x32_bf16 v[78:81], v[146:149], v[220:223], 0
	v_mfma_f32_16x16x32_bf16 v[70:73], v[154:157], v[220:223], 0
	v_mfma_f32_16x16x32_bf16 v[126:129], v[150:153], v[182:185], v[126:129]
	v_mfma_f32_16x16x32_bf16 v[118:121], v[158:161], v[182:185], v[118:121]
	v_mfma_f32_16x16x32_bf16 v[110:113], v[150:153], v[190:193], v[110:113]
	v_mfma_f32_16x16x32_bf16 v[102:105], v[158:161], v[190:193], v[102:105]
	v_mfma_f32_16x16x32_bf16 v[94:97], v[150:153], v[206:209], v[94:97]
	v_mfma_f32_16x16x32_bf16 v[86:89], v[158:161], v[206:209], v[86:89]
	v_mfma_f32_16x16x32_bf16 v[78:81], v[150:153], v[224:227], v[78:81]
	v_mfma_f32_16x16x32_bf16 v[70:73], v[158:161], v[224:227], v[70:73]
	s_setprio 0
	s_setprio 1
	v_mfma_f32_16x16x32_bf16 v[122:125], v[162:165], v[178:181], 0
	v_mfma_f32_16x16x32_bf16 v[114:117], v[170:173], v[178:181], 0
	v_mfma_f32_16x16x32_bf16 v[106:109], v[162:165], v[186:189], 0
	v_mfma_f32_16x16x32_bf16 v[98:101], v[170:173], v[186:189], 0
	v_mfma_f32_16x16x32_bf16 v[90:93], v[162:165], v[202:205], 0
	v_mfma_f32_16x16x32_bf16 v[82:85], v[170:173], v[202:205], 0
	v_mfma_f32_16x16x32_bf16 v[74:77], v[162:165], v[220:223], 0
	v_mfma_f32_16x16x32_bf16 v[66:69], v[170:173], v[220:223], 0
	v_mfma_f32_16x16x32_bf16 v[122:125], v[166:169], v[182:185], v[122:125]
	v_mfma_f32_16x16x32_bf16 v[114:117], v[174:177], v[182:185], v[114:117]
	v_mfma_f32_16x16x32_bf16 v[106:109], v[166:169], v[190:193], v[106:109]
	v_mfma_f32_16x16x32_bf16 v[98:101], v[174:177], v[190:193], v[98:101]
	v_mfma_f32_16x16x32_bf16 v[90:93], v[166:169], v[206:209], v[90:93]
	v_mfma_f32_16x16x32_bf16 v[82:85], v[174:177], v[206:209], v[82:85]
	v_mfma_f32_16x16x32_bf16 v[74:77], v[166:169], v[224:227], v[74:77]
	v_mfma_f32_16x16x32_bf16 v[66:69], v[174:177], v[224:227], v[66:69]
	s_setprio 0
	s_barrier
	s_add_i32 s51, s51, s36
	v_lshl_add_u64 v[140:141], s[20:21], 0, v[0:1]
	s_mov_b32 m0, s51
	ds_read_b128 v[178:181], v145 offset:16384
	ds_read_b128 v[182:185], v145 offset:17408
	ds_read_b128 v[186:189], v145 offset:18432
	ds_read_b128 v[190:193], v145 offset:19456
	ds_read_b128 v[202:205], v145 offset:20480
	ds_read_b128 v[206:209], v145 offset:21504
	ds_read_b128 v[220:223], v145 offset:22528
	ds_read_b128 v[224:227], v145 offset:23552
	global_load_lds_dwordx4 v[140:141], off
	s_add_i32 m0, s51, 0x2000
	s_add_u32 s52, s20, 0x40000
	v_lshl_add_u64 v[194:195], s[20:21], 0, v[130:131]
	s_addc_u32 s53, s21, 0
	s_add_i32 s51, s54, s36
	global_load_lds_dwordx4 v[194:195], off
	v_lshl_add_u64 v[198:199], s[52:53], 0, v[0:1]
	s_mov_b32 m0, s51
	v_lshl_add_u64 v[200:201], s[28:29], 0, v[132:133]
	global_load_lds_dwordx4 v[198:199], off
	v_lshl_add_u64 v[198:199], s[52:53], 0, v[130:131]
	s_add_i32 m0, s51, 0x2000
	s_nop 0
	global_load_lds_dwordx4 v[198:199], off
	v_lshl_add_u64 v[198:199], s[28:29], 0, v[134:135]
	s_mov_b32 m0, s38
	s_nop 0
	global_load_lds_dwordx4 v[198:199], off
	s_mov_b32 m0, s39
	s_nop 0
	global_load_lds_dwordx4 v[200:201], off
	s_waitcnt vmcnt(8)
	s_waitcnt lgkmcnt(0)
	s_barrier
	s_setprio 1
	s_waitcnt lgkmcnt(0)
	v_mfma_f32_16x16x32_bf16 v[62:65], v[146:149], v[178:181], 0
	v_mfma_f32_16x16x32_bf16 v[54:57], v[154:157], v[178:181], 0
	v_mfma_f32_16x16x32_bf16 v[46:49], v[146:149], v[186:189], 0
	v_mfma_f32_16x16x32_bf16 v[38:41], v[154:157], v[186:189], 0
	v_mfma_f32_16x16x32_bf16 v[30:33], v[146:149], v[202:205], 0
	v_mfma_f32_16x16x32_bf16 v[22:25], v[154:157], v[202:205], 0
	v_mfma_f32_16x16x32_bf16 v[14:17], v[146:149], v[220:223], 0
	v_mfma_f32_16x16x32_bf16 v[6:9], v[154:157], v[220:223], 0
	v_mfma_f32_16x16x32_bf16 v[62:65], v[150:153], v[182:185], v[62:65]
	v_mfma_f32_16x16x32_bf16 v[54:57], v[158:161], v[182:185], v[54:57]
	v_mfma_f32_16x16x32_bf16 v[46:49], v[150:153], v[190:193], v[46:49]
	v_mfma_f32_16x16x32_bf16 v[38:41], v[158:161], v[190:193], v[38:41]
	v_mfma_f32_16x16x32_bf16 v[30:33], v[150:153], v[206:209], v[30:33]
	v_mfma_f32_16x16x32_bf16 v[22:25], v[158:161], v[206:209], v[22:25]
	v_mfma_f32_16x16x32_bf16 v[14:17], v[150:153], v[224:227], v[14:17]
	v_mfma_f32_16x16x32_bf16 v[6:9], v[158:161], v[224:227], v[6:9]
	s_setprio 0
	s_setprio 1
	v_mfma_f32_16x16x32_bf16 v[58:61], v[162:165], v[178:181], 0
	v_mfma_f32_16x16x32_bf16 v[50:53], v[170:173], v[178:181], 0
	v_mfma_f32_16x16x32_bf16 v[42:45], v[162:165], v[186:189], 0
	v_mfma_f32_16x16x32_bf16 v[34:37], v[170:173], v[186:189], 0
	v_mfma_f32_16x16x32_bf16 v[26:29], v[162:165], v[202:205], 0
	v_mfma_f32_16x16x32_bf16 v[18:21], v[170:173], v[202:205], 0
	v_mfma_f32_16x16x32_bf16 v[10:13], v[162:165], v[220:223], 0
	v_mfma_f32_16x16x32_bf16 v[2:5], v[170:173], v[220:223], 0
	v_mfma_f32_16x16x32_bf16 v[58:61], v[166:169], v[182:185], v[58:61]
	v_mfma_f32_16x16x32_bf16 v[50:53], v[174:177], v[182:185], v[50:53]
	v_mfma_f32_16x16x32_bf16 v[42:45], v[166:169], v[190:193], v[42:45]
	v_mfma_f32_16x16x32_bf16 v[34:37], v[174:177], v[190:193], v[34:37]
	v_mfma_f32_16x16x32_bf16 v[26:29], v[166:169], v[206:209], v[26:29]
	v_mfma_f32_16x16x32_bf16 v[18:21], v[174:177], v[206:209], v[18:21]
	v_mfma_f32_16x16x32_bf16 v[10:13], v[166:169], v[224:227], v[10:13]
	v_mfma_f32_16x16x32_bf16 v[2:5], v[174:177], v[224:227], v[2:5]
	s_setprio 0
	s_barrier
	s_add_i32 s51, 0, 0x18000
	s_add_i32 s52, 0, 0x1c000
	v_add_u32_e32 v158, s51, v143
	v_add_u32_e32 v174, s52, v143
	ds_read_b128 v[146:149], v158
	ds_read_b128 v[150:153], v158 offset:1024
	ds_read_b128 v[154:157], v158 offset:2048
	ds_read_b128 v[158:161], v158 offset:3072
	ds_read_b128 v[162:165], v174
	ds_read_b128 v[166:169], v174 offset:1024
	ds_read_b128 v[170:173], v174 offset:2048
	ds_read_b128 v[174:177], v174 offset:3072
	s_add_u32 s28, s28, 0x40000
	s_addc_u32 s29, s29, 0
	s_mov_b32 m0, s40
	v_lshl_add_u64 v[210:211], s[28:29], 0, v[134:135]
	ds_read_b128 v[178:181], v145 offset:32768
	ds_read_b128 v[182:185], v145 offset:33792
	ds_read_b128 v[186:189], v145 offset:34816
	ds_read_b128 v[190:193], v145 offset:35840
	ds_read_b128 v[202:205], v145 offset:36864
	ds_read_b128 v[206:209], v145 offset:37888
	ds_read_b128 v[220:223], v145 offset:38912
	ds_read_b128 v[224:227], v145 offset:39936
	global_load_lds_dwordx4 v[210:211], off
	v_lshl_add_u64 v[210:211], s[28:29], 0, v[132:133]
	s_mov_b32 m0, s41
	s_nop 0
	global_load_lds_dwordx4 v[210:211], off
	s_waitcnt vmcnt(8)
	s_waitcnt lgkmcnt(0)
	s_barrier
	s_setprio 1
	s_waitcnt lgkmcnt(0)
	v_mfma_f32_16x16x32_bf16 v[126:129], v[146:149], v[178:181], v[126:129]
	v_mfma_f32_16x16x32_bf16 v[118:121], v[154:157], v[178:181], v[118:121]
	v_mfma_f32_16x16x32_bf16 v[110:113], v[146:149], v[186:189], v[110:113]
	v_mfma_f32_16x16x32_bf16 v[102:105], v[154:157], v[186:189], v[102:105]
	v_mfma_f32_16x16x32_bf16 v[94:97], v[146:149], v[202:205], v[94:97]
	v_mfma_f32_16x16x32_bf16 v[86:89], v[154:157], v[202:205], v[86:89]
	v_mfma_f32_16x16x32_bf16 v[78:81], v[146:149], v[220:223], v[78:81]
	v_mfma_f32_16x16x32_bf16 v[70:73], v[154:157], v[220:223], v[70:73]
	v_mfma_f32_16x16x32_bf16 v[126:129], v[150:153], v[182:185], v[126:129]
	v_mfma_f32_16x16x32_bf16 v[118:121], v[158:161], v[182:185], v[118:121]
	v_mfma_f32_16x16x32_bf16 v[110:113], v[150:153], v[190:193], v[110:113]
	v_mfma_f32_16x16x32_bf16 v[102:105], v[158:161], v[190:193], v[102:105]
	v_mfma_f32_16x16x32_bf16 v[94:97], v[150:153], v[206:209], v[94:97]
	v_mfma_f32_16x16x32_bf16 v[86:89], v[158:161], v[206:209], v[86:89]
	v_mfma_f32_16x16x32_bf16 v[78:81], v[150:153], v[224:227], v[78:81]
	v_mfma_f32_16x16x32_bf16 v[70:73], v[158:161], v[224:227], v[70:73]
	s_setprio 0
	s_setprio 1
	v_mfma_f32_16x16x32_bf16 v[122:125], v[162:165], v[178:181], v[122:125]
	v_mfma_f32_16x16x32_bf16 v[114:117], v[170:173], v[178:181], v[114:117]
	v_mfma_f32_16x16x32_bf16 v[106:109], v[162:165], v[186:189], v[106:109]
	v_mfma_f32_16x16x32_bf16 v[98:101], v[170:173], v[186:189], v[98:101]
	v_mfma_f32_16x16x32_bf16 v[90:93], v[162:165], v[202:205], v[90:93]
	v_mfma_f32_16x16x32_bf16 v[82:85], v[170:173], v[202:205], v[82:85]
	v_mfma_f32_16x16x32_bf16 v[74:77], v[162:165], v[220:223], v[74:77]
	v_mfma_f32_16x16x32_bf16 v[66:69], v[170:173], v[220:223], v[66:69]
	v_mfma_f32_16x16x32_bf16 v[122:125], v[166:169], v[182:185], v[122:125]
	v_mfma_f32_16x16x32_bf16 v[114:117], v[174:177], v[182:185], v[114:117]
	v_mfma_f32_16x16x32_bf16 v[106:109], v[166:169], v[190:193], v[106:109]
	v_mfma_f32_16x16x32_bf16 v[98:101], v[174:177], v[190:193], v[98:101]
	v_mfma_f32_16x16x32_bf16 v[90:93], v[166:169], v[206:209], v[90:93]
	v_mfma_f32_16x16x32_bf16 v[82:85], v[174:177], v[206:209], v[82:85]
	v_mfma_f32_16x16x32_bf16 v[74:77], v[166:169], v[224:227], v[74:77]
	v_mfma_f32_16x16x32_bf16 v[66:69], v[174:177], v[224:227], v[66:69]
	s_setprio 0
	s_barrier
	s_add_i32 s28, s51, s36
	v_lshl_add_u64 v[140:141], v[140:141], 0, s[84:85]
	s_mov_b32 m0, s28
	ds_read_b128 v[178:181], v145 offset:49152
	ds_read_b128 v[182:185], v145 offset:50176
	ds_read_b128 v[186:189], v145 offset:51200
	ds_read_b128 v[190:193], v145 offset:52224
	ds_read_b128 v[202:205], v145 offset:53248
	ds_read_b128 v[206:209], v145 offset:54272
	ds_read_b128 v[220:223], v145 offset:55296
	ds_read_b128 v[224:227], v145 offset:56320
	global_load_lds_dwordx4 v[140:141], off
	s_add_i32 m0, s28, 0x2000
	s_add_u32 s20, s20, 0x40080
	v_lshl_add_u64 v[140:141], v[194:195], 0, s[84:85]
	s_addc_u32 s21, s21, 0
	s_add_i32 s28, s52, s36
	global_load_lds_dwordx4 v[140:141], off
	v_lshl_add_u64 v[140:141], s[20:21], 0, v[0:1]
	s_mov_b32 m0, s28
	s_nop 0
	global_load_lds_dwordx4 v[140:141], off
	v_lshl_add_u64 v[140:141], s[20:21], 0, v[130:131]
	s_add_i32 m0, s28, 0x2000
	s_nop 0
	global_load_lds_dwordx4 v[140:141], off
	v_lshl_add_u64 v[140:141], v[198:199], 0, s[84:85]
	s_mov_b32 m0, s76
	s_nop 0
	global_load_lds_dwordx4 v[140:141], off
	v_lshl_add_u64 v[140:141], v[200:201], 0, s[84:85]
	s_mov_b32 m0, s77
	s_nop 0
	global_load_lds_dwordx4 v[140:141], off
	s_waitcnt vmcnt(8)
	s_waitcnt lgkmcnt(0)
	s_barrier
	s_setprio 1
	s_waitcnt lgkmcnt(0)
	v_mfma_f32_16x16x32_bf16 v[62:65], v[146:149], v[178:181], v[62:65]
	v_mfma_f32_16x16x32_bf16 v[54:57], v[154:157], v[178:181], v[54:57]
	v_mfma_f32_16x16x32_bf16 v[46:49], v[146:149], v[186:189], v[46:49]
	v_mfma_f32_16x16x32_bf16 v[38:41], v[154:157], v[186:189], v[38:41]
	v_mfma_f32_16x16x32_bf16 v[30:33], v[146:149], v[202:205], v[30:33]
	v_mfma_f32_16x16x32_bf16 v[22:25], v[154:157], v[202:205], v[22:25]
	v_mfma_f32_16x16x32_bf16 v[14:17], v[146:149], v[220:223], v[14:17]
	v_mfma_f32_16x16x32_bf16 v[6:9], v[154:157], v[220:223], v[6:9]
	v_mfma_f32_16x16x32_bf16 v[62:65], v[150:153], v[182:185], v[62:65]
	v_mfma_f32_16x16x32_bf16 v[54:57], v[158:161], v[182:185], v[54:57]
	v_mfma_f32_16x16x32_bf16 v[46:49], v[150:153], v[190:193], v[46:49]
	v_mfma_f32_16x16x32_bf16 v[38:41], v[158:161], v[190:193], v[38:41]
	v_mfma_f32_16x16x32_bf16 v[30:33], v[150:153], v[206:209], v[30:33]
	v_mfma_f32_16x16x32_bf16 v[22:25], v[158:161], v[206:209], v[22:25]
	v_mfma_f32_16x16x32_bf16 v[14:17], v[150:153], v[224:227], v[14:17]
	v_mfma_f32_16x16x32_bf16 v[6:9], v[158:161], v[224:227], v[6:9]
	s_setprio 0
	s_setprio 1
	v_mfma_f32_16x16x32_bf16 v[58:61], v[162:165], v[178:181], v[58:61]
	v_mfma_f32_16x16x32_bf16 v[50:53], v[170:173], v[178:181], v[50:53]
	v_mfma_f32_16x16x32_bf16 v[42:45], v[162:165], v[186:189], v[42:45]
	v_mfma_f32_16x16x32_bf16 v[34:37], v[170:173], v[186:189], v[34:37]
	v_mfma_f32_16x16x32_bf16 v[26:29], v[162:165], v[202:205], v[26:29]
	v_mfma_f32_16x16x32_bf16 v[18:21], v[170:173], v[202:205], v[18:21]
	v_mfma_f32_16x16x32_bf16 v[10:13], v[162:165], v[220:223], v[10:13]
	v_mfma_f32_16x16x32_bf16 v[2:5], v[170:173], v[220:223], v[2:5]
	v_mfma_f32_16x16x32_bf16 v[58:61], v[166:169], v[182:185], v[58:61]
	v_mfma_f32_16x16x32_bf16 v[50:53], v[174:177], v[182:185], v[50:53]
	v_mfma_f32_16x16x32_bf16 v[42:45], v[166:169], v[190:193], v[42:45]
	v_mfma_f32_16x16x32_bf16 v[34:37], v[174:177], v[190:193], v[34:37]
	v_mfma_f32_16x16x32_bf16 v[26:29], v[166:169], v[206:209], v[26:29]
	v_mfma_f32_16x16x32_bf16 v[18:21], v[174:177], v[206:209], v[18:21]
	v_mfma_f32_16x16x32_bf16 v[10:13], v[166:169], v[224:227], v[10:13]
	v_mfma_f32_16x16x32_bf16 v[2:5], v[174:177], v[224:227], v[2:5]
	s_setprio 0
	s_barrier
	s_add_i32 s50, s50, 2
	s_add_u32 s4, s4, 0x100
	s_addc_u32 s5, s5, 0
	s_add_u32 s48, s48, 0x100
	s_addc_u32 s49, s49, 0
	s_cmp_gt_u32 s50, 13
	s_cbranch_scc1 .Lpeel_exit_swi
	.p2alignl 6, 3212836864
